# adds: P1 epilogue next-unit row-scale reductions batched (8 independent shuffle chains issued together)
# baseline (speedup 1.0000x reference)
;     __device__ __forceinline__ void operator()(const f32x4 (&acc)[2][2][4][2], const pg8::Unit& u, int wr, int wc, int fr, int fq) const {
;     ...
;         if (hasn) {
; #pragma unroll
;             for (int q = 0; q < 8; ++q) { float s_ = (np[q][0] + np[q][1]) + (np[q][2] + np[q][3]); s_ += __shfl_xor(s_, 16); s_ += __shfl_xor(s_, 32);
;                 if (fq == 0) slot[q * 16 + fr] = rsqrtf(s_ * (1.0f / 1024.0f) + EPS); }
;         }
.LBB0_426:
	v_and_b32_e32 v3, 64, v222
	v_xor_b32_e32 v2, 16, v222
	v_add_u32_e32 v3, 64, v3
	v_cmp_lt_i32_e32 vcc, v2, v3
	v_xor_b32_e32 v6, 32, v222
	s_nop 1
	v_cndmask_b32_e32 v2, v222, v2, vcc
	v_cmp_lt_i32_e32 vcc, v6, v3
	v_lshlrev_b32_e32 v2, 2, v2
	s_nop 1
	v_cndmask_b32_e32 v3, v222, v6, vcc
	v_lshlrev_b32_e32 v3, 2, v3
	v_add_f32_e32 v110, v110, v111
	v_add_f32_e32 v112, v112, v113
	v_add_f32_e32 v110, v110, v112
	v_add_f32_e32 v102, v102, v103
	v_add_f32_e32 v104, v104, v105
	v_add_f32_e32 v102, v102, v104
	v_add_f32_e32 v98, v98, v99
	v_add_f32_e32 v100, v100, v101
	v_add_f32_e32 v98, v98, v100
	v_add_f32_e32 v94, v94, v95
	v_add_f32_e32 v96, v96, v97
	v_add_f32_e32 v94, v94, v96
	v_add_f32_e32 v90, v90, v91
	v_add_f32_e32 v92, v92, v93
	v_add_f32_e32 v90, v90, v92
	v_add_f32_e32 v82, v82, v83
	v_add_f32_e32 v84, v84, v85
	v_add_f32_e32 v82, v82, v84
	v_add_f32_e32 v78, v78, v79
	v_add_f32_e32 v80, v80, v81
	v_add_f32_e32 v78, v78, v80
	v_add_f32_e32 v74, v74, v75
	v_add_f32_e32 v76, v76, v77
	v_add_f32_e32 v74, v74, v76
	ds_bpermute_b32 v111, v2, v110
	ds_bpermute_b32 v103, v2, v102
	ds_bpermute_b32 v99, v2, v98
	ds_bpermute_b32 v95, v2, v94
	ds_bpermute_b32 v91, v2, v90
	ds_bpermute_b32 v83, v2, v82
	ds_bpermute_b32 v79, v2, v78
	ds_bpermute_b32 v75, v2, v74
	s_waitcnt lgkmcnt(7)
	v_add_f32_e32 v110, v110, v111
	s_waitcnt lgkmcnt(6)
	v_add_f32_e32 v102, v102, v103
	s_waitcnt lgkmcnt(5)
	v_add_f32_e32 v98, v98, v99
	s_waitcnt lgkmcnt(4)
	v_add_f32_e32 v94, v94, v95
	s_waitcnt lgkmcnt(3)
	v_add_f32_e32 v90, v90, v91
	s_waitcnt lgkmcnt(2)
	v_add_f32_e32 v82, v82, v83
	s_waitcnt lgkmcnt(1)
	v_add_f32_e32 v78, v78, v79
	s_waitcnt lgkmcnt(0)
	v_add_f32_e32 v74, v74, v75
	ds_bpermute_b32 v111, v3, v110
	ds_bpermute_b32 v103, v3, v102
	ds_bpermute_b32 v99, v3, v98
	ds_bpermute_b32 v95, v3, v94
	ds_bpermute_b32 v91, v3, v90
	ds_bpermute_b32 v83, v3, v82
	ds_bpermute_b32 v79, v3, v78
	ds_bpermute_b32 v75, v3, v74
	v_cmp_eq_u32_e32 vcc, 0, v236
	s_and_saveexec_b64 s[22:23], vcc
	s_cbranch_execz .LBB0_442
	s_waitcnt lgkmcnt(7)
	v_add_f32_e32 v110, v110, v111
	v_fmamk_f32 v110, v110, 0x3a800000, v221
	v_mul_f32_e32 v111, 0x4b800000, v110
	v_cmp_gt_f32_e64 s[40:41], s91, v110
	s_nop 1
	v_cndmask_b32_e64 v110, v110, v111, s[40:41]
	v_rsq_f32_e32 v110, v110
	s_nop 0
	v_mul_f32_e32 v111, 0x45800000, v110
	v_cndmask_b32_e64 v110, v110, v111, s[40:41]
	ds_write_b32 v235, v110
	s_waitcnt lgkmcnt(6)
	v_add_f32_e32 v102, v102, v103
	v_fmamk_f32 v102, v102, 0x3a800000, v221
	v_mul_f32_e32 v103, 0x4b800000, v102
	v_cmp_gt_f32_e64 s[40:41], s91, v102
	s_nop 1
	v_cndmask_b32_e64 v102, v102, v103, s[40:41]
	v_rsq_f32_e32 v102, v102
	s_nop 0
	v_mul_f32_e32 v103, 0x45800000, v102
	v_cndmask_b32_e64 v102, v102, v103, s[40:41]
	ds_write_b32 v235, v102 offset:64
	s_waitcnt lgkmcnt(5)
	v_add_f32_e32 v98, v98, v99
	v_fmamk_f32 v98, v98, 0x3a800000, v221
	v_mul_f32_e32 v99, 0x4b800000, v98
	v_cmp_gt_f32_e64 s[40:41], s91, v98
	s_nop 1
	v_cndmask_b32_e64 v98, v98, v99, s[40:41]
	v_rsq_f32_e32 v98, v98
	s_nop 0
	v_mul_f32_e32 v99, 0x45800000, v98
	v_cndmask_b32_e64 v98, v98, v99, s[40:41]
	ds_write_b32 v235, v98 offset:128
	s_waitcnt lgkmcnt(4)
	v_add_f32_e32 v94, v94, v95
	v_fmamk_f32 v94, v94, 0x3a800000, v221
	v_mul_f32_e32 v95, 0x4b800000, v94
	v_cmp_gt_f32_e64 s[40:41], s91, v94
	s_nop 1
	v_cndmask_b32_e64 v94, v94, v95, s[40:41]
	v_rsq_f32_e32 v94, v94
	s_nop 0
	v_mul_f32_e32 v95, 0x45800000, v94
	v_cndmask_b32_e64 v94, v94, v95, s[40:41]
	ds_write_b32 v235, v94 offset:192
	s_waitcnt lgkmcnt(3)
	v_add_f32_e32 v90, v90, v91
	v_fmamk_f32 v90, v90, 0x3a800000, v221
	v_mul_f32_e32 v91, 0x4b800000, v90
	v_cmp_gt_f32_e64 s[40:41], s91, v90
	s_nop 1
	v_cndmask_b32_e64 v90, v90, v91, s[40:41]
	v_rsq_f32_e32 v90, v90
	s_nop 0
	v_mul_f32_e32 v91, 0x45800000, v90
	v_cndmask_b32_e64 v90, v90, v91, s[40:41]
	ds_write_b32 v235, v90 offset:256
	s_waitcnt lgkmcnt(2)
	v_add_f32_e32 v82, v82, v83
	v_fmamk_f32 v82, v82, 0x3a800000, v221
	v_mul_f32_e32 v83, 0x4b800000, v82
	v_cmp_gt_f32_e64 s[40:41], s91, v82
	s_nop 1
	v_cndmask_b32_e64 v82, v82, v83, s[40:41]
	v_rsq_f32_e32 v82, v82
	s_nop 0
	v_mul_f32_e32 v83, 0x45800000, v82
	v_cndmask_b32_e64 v82, v82, v83, s[40:41]
	ds_write_b32 v235, v82 offset:320
	s_waitcnt lgkmcnt(1)
	v_add_f32_e32 v78, v78, v79
	v_fmamk_f32 v78, v78, 0x3a800000, v221
	v_mul_f32_e32 v79, 0x4b800000, v78
	v_cmp_gt_f32_e64 s[40:41], s91, v78
	s_nop 1
	v_cndmask_b32_e64 v78, v78, v79, s[40:41]
	v_rsq_f32_e32 v78, v78
	s_nop 0
	v_mul_f32_e32 v79, 0x45800000, v78
	v_cndmask_b32_e64 v78, v78, v79, s[40:41]
	ds_write_b32 v235, v78 offset:384
	s_waitcnt lgkmcnt(0)
	v_add_f32_e32 v74, v74, v75
	v_fmamk_f32 v74, v74, 0x3a800000, v221
	v_mul_f32_e32 v75, 0x4b800000, v74
	v_cmp_gt_f32_e64 s[40:41], s91, v74
	s_nop 1
	v_cndmask_b32_e64 v74, v74, v75, s[40:41]
	v_rsq_f32_e32 v74, v74
	s_nop 0
	v_mul_f32_e32 v75, 0x45800000, v74
	v_cndmask_b32_e64 v74, v74, v75, s[40:41]
	ds_write_b32 v235, v74 offset:448
